# chain step: LDS fragment reads issued before the prefetch address arithmetic and global loads
# baseline (speedup 1.0000x reference)
.LBB0_165:
	v_add_u32_e32 v151, v113, v136
	v_add_u32_e32 v129, v111, v136
	v_add_u32_e32 v152, v113, v137
	ds_read_b128 v[106:109], v151 offset:40960
	ds_read_b128 v[102:105], v152 offset:40960
	v_add_u32_e32 v0, v111, v137
	ds_read_b128 v[154:157], v129 offset:32768
	ds_read_b128 v[158:161], v129 offset:34816
	ds_read_b128 v[162:165], v0 offset:32768
	ds_read_b128 v[166:169], v0 offset:34816
	ds_read_b128 v[174:177], v129 offset:36864
	ds_read_b128 v[178:181], v129 offset:38912
	ds_read_b128 v[204:207], v0 offset:36864
	ds_read_b128 v[208:211], v0 offset:38912
	ds_read_b64 v[212:213], v143
	ds_read_b64 v[214:215], v144
	ds_read_b64 v[200:201], v143 offset:4096
	ds_read_b64 v[202:203], v144 offset:4096
	s_add_i32 s11, s12, 1
	s_cmp_lt_u32 s12, 3
	s_cselect_b32 s13, 3, 39
	s_add_i32 s13, s13, s10
	s_and_b64 s[14:15], s[22:23], exec
	s_cselect_b32 s13, s11, s13
	s_add_i32 s14, s13, s7
	s_ashr_i32 s15, s14, 31
	s_lshl_b64 s[14:15], s[14:15], 3
	s_or_b64 s[28:29], s[14:15], s[26:27]
	s_lshl_b64 s[18:19], s[28:29], 14
	v_lshl_add_u64 v[62:63], v[114:115], 0, s[18:19]
	v_add_co_u32_e32 v58, vcc, s85, v62
	v_lshl_add_u64 v[78:79], v[116:117], 0, s[18:19]
	s_nop 0
	v_addc_co_u32_e32 v59, vcc, 0, v63, vcc
	v_add_co_u32_e32 v64, vcc, s37, v62
	s_lshl_b32 s16, s13, 6
	s_nop 0
	v_addc_co_u32_e32 v65, vcc, 0, v63, vcc
	v_add_co_u32_e32 v66, vcc, s33, v62
	s_lshl_b64 s[14:15], s[28:29], 13
	s_nop 0
	v_addc_co_u32_e32 v67, vcc, 0, v63, vcc
	v_add_co_u32_e32 v74, vcc, s85, v78
	s_ashr_i32 s17, s16, 31
	s_nop 0
	v_addc_co_u32_e32 v75, vcc, 0, v79, vcc
	v_add_co_u32_e32 v80, vcc, s37, v78
	v_lshl_add_u64 v[86:87], v[118:119], 0, s[14:15]
	s_nop 0
	v_addc_co_u32_e32 v81, vcc, 0, v79, vcc
	v_add_co_u32_e32 v82, vcc, s33, v78
	s_lshl_b64 s[14:15], s[16:17], 1
	s_nop 0
	v_addc_co_u32_e32 v83, vcc, 0, v79, vcc
	s_add_u32 s14, s8, s14
	v_add_co_u32_e32 v90, vcc, s85, v86
	s_addc_u32 s15, s9, s15
	s_nop 0
	v_addc_co_u32_e32 v91, vcc, 0, v87, vcc
	v_lshl_add_u64 v[94:95], s[14:15], 0, v[120:121]
	v_lshl_add_u64 v[98:99], s[14:15], 0, v[122:123]
	global_load_dwordx4 v[54:57], v[62:63], off
	s_nop 0
	global_load_dwordx4 v[58:61], v[58:59], off
	s_nop 0
	global_load_dwordx4 v[62:65], v[64:65], off
	s_nop 0
	global_load_dwordx4 v[66:69], v[66:67], off
	s_nop 0
	global_load_dwordx4 v[70:73], v[78:79], off
	s_nop 0
	global_load_dwordx4 v[74:77], v[74:75], off
	s_nop 0
	global_load_dwordx4 v[78:81], v[80:81], off
	s_nop 0
	global_load_dwordx4 v[82:85], v[82:83], off
	s_nop 0
	global_load_dwordx4 v[86:89], v[86:87], off
	s_nop 0
	global_load_dwordx4 v[90:93], v[90:91], off
	s_nop 0
	global_load_dwordx4 v[94:97], v[94:95], off
	s_nop 0
	global_load_dwordx4 v[98:101], v[98:99], off
	s_and_saveexec_b64 s[40:41], s[38:39]
	s_cbranch_execz .LBB0_167
	s_lshl_b64 s[14:15], s[28:29], 9
	v_lshl_add_u64 v[2:3], v[124:125], 0, s[14:15]
	global_load_dwordx4 v[2:5], v[2:3], off
.LBB0_167:
	s_or_b64 exec, exec, s[40:41]
	s_cmp_gt_u32 s12, 3
	ds_read_b64 v[170:171], v143 offset:8192
	ds_read_b64 v[172:173], v144 offset:8192
	ds_read_b64 v[220:221], v143 offset:12288
	ds_read_b64 v[222:223], v144 offset:12288
	ds_read_b64 v[216:217], v145
	ds_read_b64 v[218:219], v146
	ds_read_b64 v[228:229], v145 offset:4096
	ds_read_b64 v[230:231], v146 offset:4096
	ds_read_b64 v[224:225], v145 offset:8192
	ds_read_b64 v[226:227], v146 offset:8192
	ds_read_b64 v[236:237], v145 offset:12288
	ds_read_b64 v[238:239], v146 offset:12288
	s_cselect_b32 s13, 39, 3
	s_add_i32 s13, s13, s10
	s_add_i32 s13, s13, 1
	s_and_b64 s[14:15], s[22:23], exec
	s_cselect_b32 s12, s12, s13
	s_waitcnt lgkmcnt(12)
	v_mfma_f32_16x16x32_bf16 v[154:157], v[106:109], v[154:157], 0
	v_mfma_f32_16x16x32_bf16 v[158:161], v[106:109], v[158:161], 0
	v_mfma_f32_16x16x32_bf16 v[154:157], v[102:105], v[162:165], v[154:157]
	v_mfma_f32_16x16x32_bf16 v[158:161], v[102:105], v[166:169], v[158:161]
	v_mfma_f32_16x16x32_bf16 v[162:165], v[106:109], v[174:177], 0
	v_mfma_f32_16x16x32_bf16 v[166:169], v[106:109], v[178:181], 0
	v_mfma_f32_16x16x32_bf16 v[162:165], v[102:105], v[204:207], v[162:165]
	v_mfma_f32_16x16x32_bf16 v[166:169], v[102:105], v[208:211], v[166:169]
	ds_read_b64 v[208:209], v147
	ds_read_b64 v[210:211], v148
	ds_read_b64 v[178:179], v147 offset:4096
	ds_read_b64 v[180:181], v148 offset:4096
	ds_read_b64 v[174:175], v147 offset:8192
	ds_read_b64 v[176:177], v148 offset:8192
	ds_read_b64 v[232:233], v147 offset:12288
	ds_read_b64 v[234:235], v148 offset:12288
	ds_read_b64 v[204:205], v149
	ds_read_b64 v[206:207], v150
	ds_read_b64 v[244:245], v149 offset:4096
	ds_read_b64 v[246:247], v150 offset:4096
	ds_read_b64 v[240:241], v149 offset:8192
	ds_read_b64 v[242:243], v150 offset:8192
	ds_read_b64 v[192:193], v149 offset:12288
	ds_read_b64 v[194:195], v150 offset:12288
	s_waitcnt lgkmcnt(15)
	v_mfma_f32_16x16x32_bf16 v[154:157], v[42:45], v[212:215], v[154:157]
	v_mfma_f32_16x16x32_bf16 v[158:161], v[42:45], v[200:203], v[158:161]
	v_mfma_f32_16x16x32_bf16 v[162:165], v[42:45], v[170:173], v[162:165]
	v_mfma_f32_16x16x32_bf16 v[42:45], v[42:45], v[220:223], v[166:169]
	v_mfma_f32_16x16x32_bf16 v[154:157], v[38:41], v[216:219], v[154:157]
	v_mfma_f32_16x16x32_bf16 v[158:161], v[38:41], v[228:231], v[158:161]
	v_mfma_f32_16x16x32_bf16 v[162:165], v[38:41], v[224:227], v[162:165]
	v_mfma_f32_16x16x32_bf16 v[38:41], v[38:41], v[236:239], v[42:45]
	s_nop 3
	ds_read_b128 v[42:45], v135 offset:49152
	ds_read_b128 v[166:169], v135 offset:49216
	ds_read_b128 v[170:173], v129 offset:16384
	ds_read_b128 v[200:203], v129 offset:18432
	ds_read_b128 v[212:215], v0 offset:16384
	ds_read_b128 v[216:219], v0 offset:18432
	s_waitcnt lgkmcnt(6)
	v_mfma_f32_16x16x32_bf16 v[154:157], v[22:25], v[208:211], v[154:157]
	v_mfma_f32_16x16x32_bf16 v[158:161], v[22:25], v[178:181], v[158:161]
	v_mfma_f32_16x16x32_bf16 v[162:165], v[22:25], v[174:177], v[162:165]
	v_mfma_f32_16x16x32_bf16 v[22:25], v[22:25], v[232:235], v[38:41]
	v_mfma_f32_16x16x32_bf16 v[38:41], v[18:21], v[204:207], v[154:157]
	v_mfma_f32_16x16x32_bf16 v[154:157], v[18:21], v[244:247], v[158:161]
	v_mfma_f32_16x16x32_bf16 v[158:161], v[18:21], v[240:243], v[162:165]
	v_mfma_f32_16x16x32_bf16 v[18:21], v[18:21], v[192:195], v[22:25]
	s_nop 3
	ds_read_b128 v[22:25], v135 offset:49280
	ds_read_b128 v[162:165], v135 offset:49344
	ds_read_b128 v[174:177], v129 offset:20480
	ds_read_b128 v[178:181], v129 offset:22528
	ds_read_b128 v[192:195], v0 offset:20480
	ds_read_b128 v[204:207], v0 offset:22528
	s_waitcnt lgkmcnt(0)
	v_pk_mul_f32 v[8:9], v[8:9], v[44:45]
	v_pk_mul_f32 v[6:7], v[6:7], v[42:43]
	v_pk_mul_f32 v[12:13], v[12:13], v[168:169]
	v_pk_mul_f32 v[10:11], v[10:11], v[166:167]
	v_mfma_f32_16x16x32_bf16 v[6:9], v[170:173], v[106:109], v[6:9]
	s_nop 0
	v_mfma_f32_16x16x32_bf16 v[10:13], v[200:203], v[106:109], v[10:13]
	v_mfma_f32_16x16x32_bf16 v[6:9], v[212:215], v[102:105], v[6:9]
	v_mfma_f32_16x16x32_bf16 v[10:13], v[216:219], v[102:105], v[10:13]
	s_lshl_b32 s12, s12, 6
	s_ashr_i32 s13, s12, 31
	v_lshl_add_u64 v[42:43], v[130:131], 0, s[12:13]
	v_cvt_pk_bf16_f32 v38, v38, v39
	v_cvt_pk_bf16_f32 v39, v40, v41
	v_lshlrev_b64 v[40:41], 11, v[42:43]
	v_lshl_add_u64 v[40:41], v[132:133], 0, v[40:41]
	v_add_co_u32_e32 v42, vcc, s3, v40
	global_store_dwordx2 v[40:41], v[38:39], off
	v_cvt_pk_bf16_f32 v38, v154, v155
	v_cvt_pk_bf16_f32 v39, v156, v157
	v_addc_co_u32_e32 v43, vcc, 0, v41, vcc
	global_store_dwordx2 v[42:43], v[38:39], off
	v_add_co_u32_e32 v42, vcc, s36, v40
	s_mov_b32 s12, 0x18000
	s_nop 0
	v_addc_co_u32_e32 v43, vcc, 0, v41, vcc
	v_cvt_pk_bf16_f32 v18, v18, v19
	v_cvt_pk_bf16_f32 v19, v20, v21
	v_add_co_u32_e32 v20, vcc, s12, v40
	v_cvt_pk_bf16_f32 v38, v158, v159
	v_cvt_pk_bf16_f32 v39, v160, v161
	v_addc_co_u32_e32 v21, vcc, 0, v41, vcc
	global_store_dwordx2 v[42:43], v[38:39], off
	global_store_dwordx2 v[20:21], v[18:19], off
	ds_read_b128 v[18:21], v135 offset:49408
	ds_read_b128 v[38:41], v135 offset:49472
	ds_read_b128 v[42:45], v129 offset:24576
	ds_read_b128 v[154:157], v129 offset:26624
	ds_read_b128 v[158:161], v0 offset:24576
	ds_read_b128 v[166:169], v0 offset:26624
	v_pk_mul_f32 v[16:17], v[16:17], v[24:25]
	v_pk_mul_f32 v[14:15], v[14:15], v[22:23]
	v_pk_mul_f32 v[24:25], v[28:29], v[164:165]
	v_pk_mul_f32 v[22:23], v[26:27], v[162:163]
	v_mfma_f32_16x16x32_bf16 v[14:17], v[174:177], v[106:109], v[14:17]
	s_nop 0
	v_mfma_f32_16x16x32_bf16 v[22:25], v[178:181], v[106:109], v[22:25]
	v_mfma_f32_16x16x32_bf16 v[14:17], v[192:195], v[102:105], v[14:17]
	v_mfma_f32_16x16x32_bf16 v[26:29], v[204:207], v[102:105], v[22:25]
	s_nop 5
	ds_read_b128 v[22:25], v135 offset:49536
	ds_read_b128 v[162:165], v135 offset:49600
	ds_read_b128 v[170:173], v129 offset:28672
	ds_read_b128 v[174:177], v129 offset:30720
	ds_read_b128 v[178:181], v0 offset:28672
	ds_read_b128 v[192:195], v0 offset:30720
	s_waitcnt lgkmcnt(0)
	v_pk_mul_f32 v[20:21], v[32:33], v[20:21]
	v_pk_mul_f32 v[18:19], v[30:31], v[18:19]
	s_nop 1
	v_mfma_f32_16x16x32_bf16 v[18:21], v[42:45], v[106:109], v[18:21]
	v_mfma_f32_16x16x32_bf16 v[30:33], v[158:161], v[102:105], v[18:21]
	s_nop 6
	v_mul_f32_e64 v20, v36, v40
	v_mul_f32_e64 v21, v37, v41
	v_pk_mul_f32 v[18:19], v[34:35], v[38:39]
	s_nop 1
	v_mfma_f32_16x16x32_bf16 v[18:21], v[154:157], v[106:109], v[18:21]
	v_mfma_f32_16x16x32_bf16 v[34:37], v[166:169], v[102:105], v[18:21]
	s_nop 6
	v_mul_f32_e64 v20, v52, v24
	v_mul_f32_e64 v21, v53, v25
	v_pk_mul_f32 v[18:19], v[50:51], v[22:23]
	v_pk_mul_f32 v[24:25], v[48:49], v[164:165]
	v_pk_mul_f32 v[22:23], v[46:47], v[162:163]
	v_mfma_f32_16x16x32_bf16 v[18:21], v[170:173], v[106:109], v[18:21]
	s_barrier
	v_mfma_f32_16x16x32_bf16 v[50:53], v[178:181], v[102:105], v[18:21]
	s_waitcnt vmcnt(0)
	ds_write_b128 v138, v[54:57]
	ds_write_b128 v139, v[58:61]
	ds_write_b128 v140, v[62:65]
	ds_write_b128 v141, v[66:69]
	ds_write_b128 v142, v[70:73] offset:16384
	ds_write_b128 v142, v[74:77] offset:20480
	ds_write_b128 v142, v[78:81] offset:24576
	ds_write_b128 v142, v[82:85] offset:28672
	ds_write_b128 v142, v[86:89] offset:32768
	ds_write_b128 v142, v[90:93] offset:36864
	ds_write_b128 v142, v[94:97] offset:40960
	ds_write_b128 v142, v[98:101] offset:45056
	v_mfma_f32_16x16x32_bf16 v[18:21], v[174:177], v[106:109], v[22:25]
	v_mfma_f32_16x16x32_bf16 v[46:49], v[192:195], v[102:105], v[18:21]
	s_and_saveexec_b64 s[28:29], s[38:39]
	ds_write_b128 v112, v[2:5] offset:49152
	s_or_b64 exec, exec, s[28:29]
	s_add_i32 s10, s10, -1
	v_cvt_pk_bf16_f32 v42, v6, v7
	v_cvt_pk_bf16_f32 v43, v8, v9
	v_cvt_pk_bf16_f32 v44, v10, v11
	v_cvt_pk_bf16_f32 v45, v12, v13
	v_cvt_pk_bf16_f32 v38, v14, v15
	v_cvt_pk_bf16_f32 v39, v16, v17
	v_cvt_pk_bf16_f32 v40, v26, v27
	v_cvt_pk_bf16_f32 v41, v28, v29
	v_cvt_pk_bf16_f32 v22, v30, v31
	v_cvt_pk_bf16_f32 v23, v32, v33
	v_cvt_pk_bf16_f32 v24, v34, v35
	v_cvt_pk_bf16_f32 v25, v36, v37
	v_cvt_pk_bf16_f32 v18, v50, v51
	v_cvt_pk_bf16_f32 v19, v52, v53
	v_cvt_pk_bf16_f32 v20, v46, v47
	v_cvt_pk_bf16_f32 v21, v48, v49
	s_cmp_eq_u32 s11, 35
	s_waitcnt lgkmcnt(0)
	s_barrier
	s_cbranch_scc1 .LBB0_159
	s_mov_b32 s12, s11
	s_branch .LBB0_165
